# fused-epilogue row-statistics exchange: consumer polls its row's four slots directly (negative sentinel written at kernel start), panel counter + store-ack wait removed
# speedup vs baseline: 1.0422x; 1.0016x over previous
.LBB0_4:
	s_or_b64 exec, exec, s[4:5]
	s_waitcnt lgkmcnt(0)
	v_lshl_or_b32 v2, s2, 9, v1
	v_mov_b32_e32 v4, -1
	v_mov_b32_e32 v5, -1
	v_mov_b32_e32 v6, -1
	v_mov_b32_e32 v7, -1
	v_lshlrev_b32_e32 v3, 4, v2
	s_add_u32 s4, s46, 0xfa00000
	s_addc_u32 s5, s47, 0
	global_store_dwordx4 v3, v[4:7], s[4:5]
	s_add_u32 s4, s4, 0x200000
	s_addc_u32 s5, s5, 0
	v_cmp_gt_u32_e32 vcc, 0x2000, v2
	s_and_saveexec_b64 s[6:7], vcc
	global_store_dwordx4 v3, v[4:7], s[4:5]
	s_or_b64 exec, exec, s[6:7]
	s_add_u32 s4, s46, 0x4000
	v_writelane_b32 v252, s4, 0
	s_addc_u32 s4, s47, 0
	s_cmp_lt_u32 s38, 64
	v_writelane_b32 v252, s4, 1
	s_cselect_b64 s[4:5], -1, 0
	v_writelane_b32 v252, s4, 2
	s_cmp_gt_u32 s38, 63
	s_barrier
	v_writelane_b32 v252, s5, 3
	s_mov_b64 s[4:5], -1
	s_cbranch_scc1 .LBB0_7
	s_andn2_b64 vcc, exec, s[4:5]
	s_cbranch_vccz .LBB0_8

.LBB0_640:
	s_or_b64 exec, exec, s[4:5]
	s_lshl_b32 s4, s20, 6
	v_cmp_eq_u32_e64 s[8:9], 0, v221
	s_ashr_i32 s5, s4, 31
	s_and_saveexec_b64 s[22:23], s[8:9]
	s_cbranch_execz .LBB0_642
	s_lshl_b64 s[16:17], s[4:5], 2
	v_readlane_b32 s12, v255, 2
	s_add_u32 s16, s12, s16
	v_readlane_b32 s12, v254, 61
	s_addc_u32 s17, s12, s17
	v_mov_b64_e32 v[132:133], s[16:17]

.LBB0_662:
	v_readlane_b32 s4, v255, 7
	s_lshl_b32 s12, s4, 5
	v_and_or_b32 v0, v216, 31, s12
	v_lshl_add_u32 v216, s20, 8, v0
	v_lshl_add_u32 v249, v0, 2, 0
	s_and_saveexec_b64 s[4:5], s[6:7]
	s_cbranch_execz .LBB0_664
	v_readlane_b32 s16, v254, 59
	v_ashrrev_i32_e32 v217, 31, v216
	v_readlane_b32 s17, v254, 60
	s_mov_b32 s15, 0x800000
	s_nop 0
	v_lshl_add_u64 v[230:231], v[216:217], 4, s[16:17]
	s_mov_b32 s100, 0x40000
.Lseam_poll0:
	global_load_dwordx4 v[242:245], v[230:231], off sc1
	s_waitcnt vmcnt(0)
	v_or3_b32 v0, v242, v243, v244
	v_or_b32_e32 v0, v0, v245
	v_cmp_gt_i32_e32 vcc, 0, v0
	s_cbranch_vccz .Lseam_ok0
	s_sleep 1
	s_sub_u32 s100, s100, 1
	s_cmp_lg_u32 s100, 0
	s_cbranch_scc1 .Lseam_poll0
.Lseam_ok0:
	v_add_f32_e32 v0, 0, v242
	v_add_f32_e32 v0, v0, v243
	v_add_f32_e32 v0, v0, v244
	v_add_f32_e32 v0, v0, v245
	v_fmamk_f32 v0, v0, 0x3a800000, v223
	v_cmp_gt_f32_e32 vcc, s15, v0
	v_mul_f32_e32 v217, 0x4b800000, v0
	s_nop 0
	v_cndmask_b32_e32 v0, v0, v217, vcc
	v_rsq_f32_e32 v0, v0
	s_nop 0
	v_mul_f32_e32 v217, 0x45800000, v0
	v_cndmask_b32_e32 v0, v0, v217, vcc
	ds_write_b32 v249, v0 offset:8192

.LBB0_682:
	s_or_b64 exec, exec, s[4:5]
	s_and_saveexec_b64 s[4:5], s[8:9]
	s_cbranch_execz .LBB0_684
	v_readlane_b32 s10, v255, 4
	s_add_u32 s10, s10, s24
	v_readlane_b32 s11, v255, 3
	s_addc_u32 s11, s11, s25
	s_waitcnt lgkmcnt(0)
	v_mov_b64_e32 v[162:163], s[10:11]

.LBB0_704:
	s_and_saveexec_b64 s[4:5], s[6:7]
	s_cbranch_execz .LBB0_706
	v_ashrrev_i32_e32 v217, 31, v216
	v_lshl_add_u64 v[162:163], v[216:217], 4, s[34:35]
	s_mov_b32 s100, 0x40000
.Lseam_poll1:
	global_load_dwordx4 v[242:245], v[162:163], off sc1
	s_mov_b32 s6, 0x800000
	s_waitcnt vmcnt(0)
	v_or3_b32 v164, v242, v243, v244
	v_or_b32_e32 v164, v164, v245
	v_cmp_gt_i32_e32 vcc, 0, v164
	s_cbranch_vccz .Lseam_ok1
	s_sleep 1
	s_sub_u32 s100, s100, 1
	s_cmp_lg_u32 s100, 0
	s_cbranch_scc1 .Lseam_poll1
.Lseam_ok1:
	v_add_f32_e32 v164, 0, v242
	v_add_f32_e32 v164, v164, v243
	v_add_f32_e32 v164, v164, v244
	v_add_f32_e32 v162, v164, v245
	v_fmamk_f32 v162, v162, 0x3a800000, v223
	v_cmp_gt_f32_e32 vcc, s6, v162
	v_mul_f32_e32 v163, 0x4b800000, v162
	s_nop 0
	v_cndmask_b32_e32 v162, v162, v163, vcc
	v_rsq_f32_e32 v162, v162
	s_nop 0
	v_mul_f32_e32 v163, 0x45800000, v162
	v_cndmask_b32_e32 v162, v162, v163, vcc
	ds_write_b32 v249, v162 offset:8192

.LBB0_745:
	s_or_b64 exec, exec, s[4:5]
	s_lshl_b32 s4, s20, 6
	v_cmp_eq_u32_e64 s[8:9], 0, v248
	s_ashr_i32 s5, s4, 31
	s_and_saveexec_b64 s[24:25], s[8:9]
	s_cbranch_execz .LBB0_747
	s_lshl_b64 s[16:17], s[4:5], 2
	v_readlane_b32 s15, v255, 2
	s_add_u32 s16, s15, s16
	v_readlane_b32 s15, v254, 61
	s_addc_u32 s17, s15, s17
	v_mov_b64_e32 v[132:133], s[16:17]

.LBB0_767:
	v_readlane_b32 s4, v255, 7
	s_lshl_b32 s15, s4, 5
	v_and_or_b32 v0, v216, 31, s15
	v_lshl_add_u32 v216, s20, 8, v0
	v_lshl_add_u32 v251, v0, 2, 0
	s_and_saveexec_b64 s[4:5], s[6:7]
	s_cbranch_execz .LBB0_769
	v_readlane_b32 s16, v254, 59
	v_ashrrev_i32_e32 v217, 31, v216
	v_readlane_b32 s17, v254, 60
	s_nop 1
	v_lshl_add_u64 v[230:231], v[216:217], 4, s[16:17]
	s_mov_b32 s100, 0x40000
.Lseam_poll2:
	global_load_dwordx4 v[242:245], v[230:231], off sc1
	s_mov_b32 s16, 0x800000
	s_waitcnt vmcnt(0)
	v_or3_b32 v0, v242, v243, v244
	v_or_b32_e32 v0, v0, v245
	v_cmp_gt_i32_e32 vcc, 0, v0
	s_cbranch_vccz .Lseam_ok2
	s_sleep 1
	s_sub_u32 s100, s100, 1
	s_cmp_lg_u32 s100, 0
	s_cbranch_scc1 .Lseam_poll2
.Lseam_ok2:
	v_add_f32_e32 v0, 0, v242
	v_add_f32_e32 v0, v0, v243
	v_add_f32_e32 v0, v0, v244
	v_add_f32_e32 v0, v0, v245
	v_fmamk_f32 v0, v0, 0x3a800000, v223
	v_cmp_gt_f32_e32 vcc, s16, v0
	v_mul_f32_e32 v217, 0x4b800000, v0
	s_nop 0
	v_cndmask_b32_e32 v0, v0, v217, vcc
	v_rsq_f32_e32 v0, v0
	s_nop 0
	v_mul_f32_e32 v217, 0x45800000, v0
	v_cndmask_b32_e32 v0, v0, v217, vcc
	ds_write_b32 v251, v0 offset:8192

.LBB0_787:
	s_or_b64 exec, exec, s[4:5]
	s_and_saveexec_b64 s[4:5], s[8:9]
	s_cbranch_execz .LBB0_789
	v_readlane_b32 s10, v255, 4
	s_add_u32 s10, s10, s22
	v_readlane_b32 s11, v255, 3
	s_addc_u32 s11, s11, s23
	s_waitcnt lgkmcnt(0)
	v_mov_b64_e32 v[162:163], s[10:11]

.Lseam_ok3:
	v_add_f32_e32 v164, 0, v242
	v_add_f32_e32 v164, v164, v243
	v_add_f32_e32 v164, v164, v244
	v_add_f32_e32 v162, v164, v245
	v_fmamk_f32 v162, v162, 0x3a800000, v223
	v_cmp_gt_f32_e32 vcc, s6, v162
	v_mul_f32_e32 v163, 0x4b800000, v162
	s_nop 0
	v_cndmask_b32_e32 v162, v162, v163, vcc
	v_rsq_f32_e32 v162, v162
	s_nop 0
	v_mul_f32_e32 v163, 0x45800000, v162
	v_cndmask_b32_e32 v162, v162, v163, vcc
	ds_write_b32 v251, v162 offset:8192

.LBB0_1029:
	s_or_b64 exec, exec, s[8:9]
	s_mulk_i32 s12, 0x1100
	s_lshl_b64 s[8:9], s[12:13], 2
	v_readlane_b32 s15, v253, 2
	s_add_u32 s15, s15, s8
	v_readlane_b32 s8, v253, 3
	s_addc_u32 s25, s8, s9
	s_lshl_b32 s20, s16, 6
	v_cmp_eq_u32_e64 s[8:9], 0, v221
	s_ashr_i32 s21, s20, 31
	s_and_saveexec_b64 s[18:19], s[8:9]
	s_cbranch_execz .LBB0_1031
	s_lshl_b64 s[22:23], s[20:21], 2
	s_add_u32 s22, s15, s22
	s_addc_u32 s23, s25, s23
	v_mov_b64_e32 v[132:133], s[22:23]

.LBB0_1051:
	s_lshl_b32 s15, s31, 5
	v_and_or_b32 v0, v216, 31, s15
	v_lshl_add_u32 v216, s16, 8, v0
	v_lshl_add_u32 v249, v0, 2, 0
	s_and_saveexec_b64 s[24:25], s[6:7]
	s_cbranch_execz .LBB0_1053
	v_ashrrev_i32_e32 v217, 31, v216
	v_lshl_add_u64 v[226:227], v[216:217], 4, s[4:5]
	s_mov_b32 s100, 0x40000
.Lseam_poll4:
	global_load_dwordx4 v[242:245], v[226:227], off sc1
	s_mov_b32 s4, 0x800000
	s_waitcnt vmcnt(0)
	v_or3_b32 v0, v242, v243, v244
	v_or_b32_e32 v0, v0, v245
	v_cmp_gt_i32_e32 vcc, 0, v0
	s_cbranch_vccz .Lseam_ok4
	s_sleep 1
	s_sub_u32 s100, s100, 1
	s_cmp_lg_u32 s100, 0
	s_cbranch_scc1 .Lseam_poll4
.Lseam_ok4:
	v_add_f32_e32 v0, 0, v242
	v_add_f32_e32 v0, v0, v243
	v_add_f32_e32 v0, v0, v244
	v_add_f32_e32 v0, v0, v245
	v_fmamk_f32 v0, v0, 0x3a800000, v223
	v_cmp_gt_f32_e32 vcc, s4, v0
	v_mul_f32_e32 v217, 0x4b800000, v0
	s_nop 0
	v_cndmask_b32_e32 v0, v0, v217, vcc
	v_rsq_f32_e32 v0, v0
	s_nop 0
	v_mul_f32_e32 v217, 0x45800000, v0
	v_cndmask_b32_e32 v0, v0, v217, vcc
	ds_write_b32 v249, v0 offset:8192

.LBB0_1071:
	s_or_b64 exec, exec, s[10:11]
	s_addk_i32 s12, 0x1100
	s_lshl_b64 s[10:11], s[12:13], 2
	v_readlane_b32 s12, v253, 2
	s_add_u32 s12, s12, s10
	v_readlane_b32 s10, v253, 3
	s_addc_u32 s14, s10, s11
	s_and_saveexec_b64 s[10:11], s[8:9]
	s_cbranch_execz .LBB0_1073
	s_add_u32 s16, s12, s20
	s_addc_u32 s17, s14, s21
	s_waitcnt lgkmcnt(0)
	v_mov_b64_e32 v[162:163], s[16:17]

.LBB0_1093:
	s_and_saveexec_b64 s[8:9], s[6:7]
	s_cbranch_execz .LBB0_1095
	v_ashrrev_i32_e32 v217, 31, v216
	v_lshl_add_u64 v[162:163], v[216:217], 4, s[4:5]
	s_mov_b32 s100, 0x40000
.Lseam_poll5:
	global_load_dwordx4 v[242:245], v[162:163], off sc1
	s_mov_b32 s4, 0x800000
	s_waitcnt vmcnt(0)
	v_or3_b32 v164, v242, v243, v244
	v_or_b32_e32 v164, v164, v245
	v_cmp_gt_i32_e32 vcc, 0, v164
	s_cbranch_vccz .Lseam_ok5
	s_sleep 1
	s_sub_u32 s100, s100, 1
	s_cmp_lg_u32 s100, 0
	s_cbranch_scc1 .Lseam_poll5
.Lseam_ok5:
	v_add_f32_e32 v164, 0, v242
	v_add_f32_e32 v164, v164, v243
	v_add_f32_e32 v164, v164, v244
	v_add_f32_e32 v162, v164, v245
	v_fmamk_f32 v162, v162, 0x3a800000, v223
	v_cmp_gt_f32_e32 vcc, s4, v162
	v_mul_f32_e32 v163, 0x4b800000, v162
	s_nop 0
	v_cndmask_b32_e32 v162, v162, v163, vcc
	v_rsq_f32_e32 v162, v162
	s_nop 0
	v_mul_f32_e32 v163, 0x45800000, v162
	v_cndmask_b32_e32 v162, v162, v163, vcc
	ds_write_b32 v249, v162 offset:8192

.LBB0_1251:
	s_or_b64 exec, exec, s[6:7]
	s_lshl_b32 s16, s10, 6
	v_cmp_eq_u32_e64 s[6:7], 0, v0
	s_ashr_i32 s17, s16, 31
	s_and_saveexec_b64 s[8:9], s[6:7]
	s_cbranch_execz .LBB0_1253
	s_lshl_b64 s[18:19], s[16:17], 2
	v_readlane_b32 s11, v253, 50
	s_add_u32 s18, s11, s18
	v_readlane_b32 s11, v253, 51
	s_addc_u32 s19, s11, s19
	s_waitcnt lgkmcnt(0)
	v_mov_b64_e32 v[132:133], s[18:19]
.LBB0_1253:
	s_or_b64 exec, exec, s[8:9]
	s_lshl_b32 s15, s27, 5
	s_lshl_b32 s14, s14, 8
	v_lshrrev_b32_e32 v0, 1, v216
	s_ashr_i32 s11, s10, 31
	s_or_b32 s14, s14, s15
	s_lshr_b32 s18, s10, 4
	s_lshl_b64 s[8:9], s[10:11], 18
	v_and_or_b32 v134, v0, 24, s14
	v_ashrrev_i32_e32 v131, 31, v130
	s_lshl_b64 s[14:15], s[10:11], 19
	v_readlane_b32 s20, v253, 4
	v_lshlrev_b64 v[130:131], 10, v[130:131]
	v_ashrrev_i32_e32 v135, 31, v134
	v_readlane_b32 s21, v253, 5
	s_add_u32 s14, s20, s14
	v_lshl_add_u64 v[214:215], v[130:131], 0, v[134:135]
	s_addc_u32 s15, s21, s15
	v_lshl_add_u64 v[130:131], v[214:215], 1, s[14:15]
	s_mov_b32 s11, 0x8000
	s_waitcnt lgkmcnt(0)
	v_add_co_u32_e32 v132, vcc, s11, v130
	s_mov_b32 s11, 0x10000
	s_nop 0
	v_addc_co_u32_e32 v133, vcc, 0, v131, vcc
	flat_load_dwordx4 v[206:209], v[130:131]
	flat_load_dwordx4 v[202:205], v[130:131] offset:256
	flat_load_dwordx4 v[198:201], v[132:133]
	flat_load_dwordx4 v[194:197], v[132:133] offset:256
	v_add_co_u32_e32 v132, vcc, s11, v130
	s_mov_b32 s11, 0x18000
	s_nop 0
	v_addc_co_u32_e32 v133, vcc, 0, v131, vcc
	flat_load_dwordx4 v[190:193], v[132:133]
	flat_load_dwordx4 v[186:189], v[132:133] offset:256
	v_add_co_u32_e32 v132, vcc, s11, v130
	s_mov_b32 s11, 0x40000
	s_nop 0
	v_addc_co_u32_e32 v133, vcc, 0, v131, vcc
	flat_load_dwordx4 v[182:185], v[132:133]
	flat_load_dwordx4 v[178:181], v[132:133] offset:256
	v_add_co_u32_e32 v132, vcc, s11, v130
	s_mov_b32 s11, 0x48000
	s_nop 0
	v_addc_co_u32_e32 v133, vcc, 0, v131, vcc
	flat_load_dwordx4 v[174:177], v[132:133]
	flat_load_dwordx4 v[170:173], v[132:133] offset:256
	v_add_co_u32_e32 v132, vcc, s11, v130
	s_mul_i32 s14, s18, 0x1800
	s_nop 0
	v_addc_co_u32_e32 v133, vcc, 0, v131, vcc
	s_mov_b32 s11, 0x50000
	s_ashr_i32 s15, s14, 31
	flat_load_dwordx4 v[166:169], v[132:133]
	flat_load_dwordx4 v[162:165], v[132:133] offset:256
	v_add_co_u32_e32 v132, vcc, s11, v130
	s_lshl_b64 s[14:15], s[14:15], 2
	v_readlane_b32 s18, v254, 57
	v_addc_co_u32_e32 v133, vcc, 0, v131, vcc
	s_mov_b32 s11, 0x58000
	v_readlane_b32 s19, v254, 58
	s_add_u32 s14, s18, s14
	v_add_co_u32_e32 v130, vcc, s11, v130
	s_addc_u32 s15, s19, s15
	s_nop 0
	v_addc_co_u32_e32 v131, vcc, 0, v131, vcc
	v_lshl_add_u64 v[134:135], v[134:135], 2, s[14:15]
	s_mov_b64 s[14:15], 0x5000
	s_movk_i32 s11, 0x5000
	v_lshl_add_u64 v[136:137], v[134:135], 0, s[14:15]
	v_add_co_u32_e32 v134, vcc, s11, v134
	flat_load_dwordx4 v[158:161], v[132:133]
	flat_load_dwordx4 v[154:157], v[132:133] offset:256
	v_addc_co_u32_e32 v135, vcc, 0, v135, vcc
	flat_load_dwordx4 v[138:141], v[130:131]
	s_nop 0
	flat_load_dwordx4 v[130:133], v[130:131] offset:256
	s_nop 0
	flat_load_dwordx4 v[146:149], v[136:137] offset:16
	flat_load_dwordx4 v[142:145], v[136:137] offset:512
	flat_load_dwordx4 v[150:153], v[134:135]
	s_nop 0
	flat_load_dwordx4 v[134:137], v[136:137] offset:528
	s_lshl_b64 s[14:15], s[16:17], 2
	v_readlane_b32 s11, v253, 50
	s_add_u32 s14, s11, s14
	v_readlane_b32 s11, v253, 51
	s_addc_u32 s15, s11, s15
	s_mov_b32 s11, 0x40001
.LBB0_1273:
	s_and_saveexec_b64 s[6:7], s[4:5]
	s_cbranch_execnz .LBB0_1274
	s_getpc_b64 s[98:99]

.LBB0_1274:
	v_and_b32_e32 v0, 31, v216
	v_lshl_or_b32 v0, s12, 5, v0
	v_lshl_add_u32 v218, s10, 8, v0
	v_readlane_b32 s4, v253, 48
	v_ashrrev_i32_e32 v219, 31, v218
	v_readlane_b32 s5, v253, 49
	v_lshl_add_u32 v0, v0, 2, 0
	s_nop 0
	v_lshl_add_u64 v[218:219], v[218:219], 4, s[4:5]
	s_mov_b32 s100, 0x40000
.Lseam_poll6:
	global_load_dwordx4 v[242:245], v[218:219], off sc1
	s_mov_b32 s4, 0x800000
	s_waitcnt vmcnt(0)
	v_or3_b32 v216, v242, v243, v244
	v_or_b32_e32 v216, v216, v245
	v_cmp_gt_i32_e32 vcc, 0, v216
	s_cbranch_vccz .Lseam_ok6
	s_sleep 1
	s_sub_u32 s100, s100, 1
	s_cmp_lg_u32 s100, 0
	s_cbranch_scc1 .Lseam_poll6
.Lseam_ok6:
	v_add_f32_e32 v216, 0, v242
	v_add_f32_e32 v216, v216, v243
	v_add_f32_e32 v216, v216, v244
	v_add_f32_e32 v216, v216, v245
	v_fmamk_f32 v216, v216, 0x3a800000, v223
	v_cmp_gt_f32_e32 vcc, s4, v216
	v_mul_f32_e32 v218, 0x4b800000, v216
	s_nop 0
	v_cndmask_b32_e32 v216, v216, v218, vcc
	v_rsq_f32_e32 v216, v216
	s_nop 0
	v_mul_f32_e32 v218, 0x45800000, v216
	v_cndmask_b32_e32 v216, v216, v218, vcc
	ds_write_b32 v0, v216 offset:8192
	s_getpc_b64 s[98:99]
